# U half time-sliced: wave-owned tokens, 8 column-slice phases in step (L2-resident slice), partial dots accumulated in LDS; no extra grid barrier, no global partials
# speedup vs baseline: 1.0311x; 1.0311x over previous
; __device__ __forceinline__ unsigned xb_ld(unsigned* p)              { return __hip_atomic_load(p, __ATOMIC_RELAXED, __HIP_MEMORY_SCOPE_AGENT); }
; __device__ __forceinline__ unsigned xb_add(unsigned* p, unsigned v) { return __hip_atomic_fetch_add(p, v, __ATOMIC_RELAXED, __HIP_MEMORY_SCOPE_AGENT); }
; #define XB_SPIN(cond, bar) do { unsigned _sp = 0; while (cond) { __builtin_amdgcn_s_sleep(1); \
;     if ((++_sp & 255u) == 0u) { if (xb_ld(&(bar)[XB_TMO])) break; if (_sp > XB_SPIN_CAP) { atomicAdd(&(bar)[XB_TMO], 1u); break; } } } } while (0)
; __device__ __forceinline__ void xcd_barrier_complete(unsigned* bar, unsigned x, unsigned& nloc, unsigned& nx) {
;     const unsigned G = gridDim.x * gridDim.y * gridDim.z;
;     unsigned sum, cnt, mine, sp = 0u;
;     for (;;) {
;         sum = 0u; cnt = 0u; mine = 0u;
; #pragma unroll
;         for (unsigned j = 0; j < 16; ++j) { const unsigned c = xb_ld(&bar[XB_XCNT(j)]); sum += c; cnt += (c > 0u) ? 1u : 0u; mine = (j == x) ? c : mine; }
; __device__ __forceinline__ void xcd_barrier(const XcdBarrier& b) {
;     asm volatile("s_waitcnt vmcnt(0)" ::: "memory");
;     __syncthreads();
;     if (threadIdx.x == 0) {
;         unsigned* bar = b.bar;
;         __builtin_amdgcn_s_waitcnt(0);
;         unsigned nloc = b.st[0], nx = b.st[1];
;         if (nloc == 0u) { xcd_barrier_complete(bar, b.x, nloc, nx); b.st[0] = nloc; b.st[1] = nx; }
;         const unsigned old = xb_add(&bar[XB_XSUB(b.x)], 1u);
;         const unsigned gen = old / nloc;
;         if (old + 1u == (gen + 1u) * nloc) {
;             __builtin_amdgcn_fence(__ATOMIC_RELEASE, "agent");
;             asm volatile("s_waitcnt vmcnt(0)" ::: "memory");
;             const unsigned og = xb_add(&bar[XB_TOP], 1u);
;             const unsigned tg = og / nx;
;             if (og + 1u == (tg + 1u) * nx) xb_add(&bar[XB_TOPGEN], 1u);
;             else XB_SPIN(xb_ld(&bar[XB_TOPGEN]) == tg, bar);
;             __builtin_amdgcn_fence(__ATOMIC_ACQUIRE, "agent");
;             xb_add(&bar[XB_XGEN(b.x)], 1u);
;             asm volatile("s_waitcnt vmcnt(0)" ::: "memory");
;         } else {
;             XB_SPIN(xb_ld(&bar[XB_XGEN(b.x)]) == gen, bar);
;             __builtin_amdgcn_fence(__ATOMIC_ACQUIRE, "agent");
;             asm volatile("s_waitcnt vmcnt(0)" ::: "memory");
;         }
;     }
;     __syncthreads();
; }
.LBB0_1040:
.Lbar_1040:
	s_mov_b64 s[42:43], s[76:77]
	s_mov_b32 s36, s69
	s_waitcnt vmcnt(0)
	s_waitcnt lgkmcnt(0)
	s_barrier
	s_and_saveexec_b64 s[40:41], s[78:79]
	s_cbranch_execz .LBB0_1084
	v_readlane_b32 s2, v252, 63
	s_waitcnt vmcnt(0) expcnt(0) lgkmcnt(0)
	s_nop 0
	v_mov_b32_e32 v1, s2
	ds_read_b32 v4, v1
	v_readlane_b32 s2, v253, 0
	s_waitcnt lgkmcnt(0)
	v_cmp_ne_u32_e32 vcc, 0, v4
	v_mov_b32_e32 v1, s2
	ds_read_b32 v2, v1
	s_cbranch_vccnz .LBB0_1055
	v_readlane_b32 s2, v252, 0
	v_readlane_b32 s3, v252, 1
	s_load_dwordx2 s[6:7], s[2:3], 0x4
	s_add_u32 s2, s42, 0x1000
	s_addc_u32 s3, s43, 0
	s_add_u32 s4, s42, 0x1100
	s_addc_u32 s5, s43, 0
	s_waitcnt lgkmcnt(0)
	s_mul_i32 s28, s6, s80
	s_add_u32 s6, s42, 0x1200
	s_mul_i32 s28, s28, s7
	s_addc_u32 s7, s43, 0
	s_add_u32 s8, s42, 0x1300
	s_addc_u32 s9, s43, 0
	s_mov_b32 s29, 1
	s_mov_b64 s[10:11], 0
	s_branch .LBB0_1045

;     DEVI int* eidx() const { return (int*)(ws + WS_EIDX); }
; #define LAS __attribute__((address_space(3)))
;     const int n16 = lane & 15, kq = lane >> 4;
;     LAS u32x2_t* pl = (LAS u32x2_t*)wl;
;     if (PART != 2) {
;     int e[NTL]; float g[NTL], s_u[NTL], s_v[NTL];
; #pragma unroll
;     for (int t = 0; t < NTL; ++t) { e[t] = eidx[(size_t)r * 128 + (tbase + t) * 16 + n16]; g[t] = gwv[(size_t)r * 128 + (tbase + t) * 16 + n16]; }
; #pragma unroll
;     for (int t = 0; t < NTL; ++t) { s_u[t] = su[e[t]]; s_v[t] = sv[e[t]]; }
;     const unsigned char* up[NTL];
; #pragma unroll
;     for (int t = 0; t < NTL; ++t) up[t] = u8 + (size_t)e[t] * D + kq * 16;
;     const unsigned char* hp = h8 + (n16 < 8 ? (size_t)0 : (size_t)M * D) + (size_t)r * D + kq * 16;
;     f32x4_t acc[NTL];
; #pragma unroll
;     for (int t = 0; t < NTL; ++t) acc[t] = (f32x4_t){0.f, 0.f, 0.f, 0.f};
;     u32x4_t b0[NTL], b1[NTL];
; #pragma unroll
;     for (int t = 0; t < NTL; ++t) { b0[t] = *(const u32x4_t*)(up[t]); b1[t] = *(const u32x4_t*)(up[t] + 64); }
; __global__ void __launch_bounds__(NTHR, 2) mega_fwd(Args a) {
;     ...
;           for (int k0 = 0; gw_ + NGW * k0 < M_P; k0 += 8) {
; #pragma unroll 1
;               for (int k = 0; k < 8; ++k) { const int tok = gw_ + NGW * (k0 + k);
;                   if (tok < M_P) peer_gather_token_t<8, 1>(q_, l_, 0, -1, (LAS float*)nullptr, GARGS, tok, lane_, (LAS unsigned char*)lds + wave * 8192 + k * 1024); }
.LBB0_1084:
	s_or_b64 exec, exec, s[40:41]
	v_readlane_b32 s2, v253, 41
	s_mov_b64 s[6:7], s[74:75]
	s_mov_b64 s[4:5], s[72:73]
	s_mov_b32 s8, s2
	v_mov_b32_e32 v1, v210
	v_readlane_b32 s48, v252, 3
	s_mov_b32 s36, s68
	s_waitcnt lgkmcnt(0)
	s_barrier
	s_cmpk_gt_i32 s48, 0x3fff
	v_and_b32_e32 v116, 15, v1
	v_and_b32_e32 v102, -16, v1
	v_lshlrev_b32_e32 v100, 4, v1
	v_cmp_gt_u32_e64 s[2:3], 16, v1
	s_mul_hi_i32 s46, s8, 0x6c000
	s_mul_i32 s47, s8, 0x6c000
	v_ashrrev_i32_e32 v103, 31, v102
	v_cmp_gt_u32_e32 vcc, 8, v116
	v_lshl_add_u32 v117, v1, 3, s85
	v_ashrrev_i32_e32 v101, 31, v100
	s_cbranch_scc1 .LBB0_1124
	s_lshl_b32 s20, s34, 9
	s_lshl_b32 s21, s34, 10
	s_lshl_b32 s11, s8, 24
	s_add_u32 s56, s6, 0x1fa42100
	s_addc_u32 s57, s7, 0
	s_add_u32 s56, s56, s11
	s_addc_u32 s57, s57, 0
	s_mov_b32 s12, s56
	s_mov_b32 s13, s57
	s_lshl_b32 s11, s48, 9
	s_add_u32 s58, s6, 0x1b292100
	s_addc_u32 s59, s7, 0
	s_add_u32 s58, s58, s11
	s_addc_u32 s59, s59, 0
	s_lshl_b32 s11, s48, 10
	s_add_u32 s60, s6, 0x2fac2100
	s_addc_u32 s61, s7, 0
	s_add_u32 s60, s60, s11
	s_addc_u32 s61, s61, 0
	s_mov_b32 s24, 0x01010101
	s_mov_b32 s25, 0x01010101
	s_mov_b32 s26, 0x02020202
	s_mov_b32 s27, 0x02020202
	s_mov_b32 s28, 0x04040404
	s_mov_b32 s29, 0x04040404
	s_mov_b32 s30, 0x08080808
	s_mov_b32 s31, 0x08080808
	s_mov_b32 s40, 0x10101010
	s_mov_b32 s41, 0x10101010
	s_mov_b32 s42, 0x20202020
	s_mov_b32 s43, 0x20202020
	s_mov_b32 s44, 0x40404040
	s_mov_b32 s45, 0x40404040
	s_mov_b32 s54, 0x80808080
	s_mov_b32 s55, 0x80808080
	v_and_b32_e32 v2, 7, v1
	v_lshrrev_b32_e32 v3, 3, v1
	v_lshlrev_b32_e32 v4, 4, v2
	v_lshlrev_b32_e32 v5, 6, v3
	v_lshlrev_b32_e32 v6, 7, v3
	v_add3_u32 v6, v6, v4, s85
	v_mov_b32_e32 v8, 0x3d000000
	v_mov_b32_e32 v9, 0x3d000000
	v_mov_b32_e32 v118, 0
	v_mov_b32_e32 v119, 0
	ds_write_b32 v6, v118 offset:4
	ds_write_b32 v6, v118 offset:12
	ds_write_b32 v6, v118 offset:1028
	ds_write_b32 v6, v118 offset:1036
	ds_write_b32 v6, v118 offset:2052
	ds_write_b32 v6, v118 offset:2060
	ds_write_b32 v6, v118 offset:3076
	ds_write_b32 v6, v118 offset:3084
	ds_write_b32 v6, v118 offset:4100
	ds_write_b32 v6, v118 offset:4108
	ds_write_b32 v6, v118 offset:5124
	ds_write_b32 v6, v118 offset:5132
	ds_write_b32 v6, v118 offset:6148
	ds_write_b32 v6, v118 offset:6156
	ds_write_b32 v6, v118 offset:7172
	ds_write_b32 v6, v118 offset:7180
	global_load_dwordx4 v[84:87], v5, s[58:59] offset:0
	global_load_dwordx4 v[88:91], v5, s[58:59] offset:16
	global_load_dwordx4 v[92:95], v5, s[58:59] offset:32
	global_load_dwordx4 v[96:99], v5, s[58:59] offset:48
	s_waitcnt vmcnt(0)
	v_lshl_add_u32 v68, v84, 10, v4
	v_lshl_add_u32 v69, v85, 10, v4
	v_lshl_add_u32 v70, v86, 10, v4
	v_lshl_add_u32 v71, v87, 10, v4
	v_lshl_add_u32 v72, v88, 10, v4
	v_lshl_add_u32 v73, v89, 10, v4
	v_lshl_add_u32 v74, v90, 10, v4
	v_lshl_add_u32 v75, v91, 10, v4
	v_lshl_add_u32 v76, v92, 10, v4
	v_lshl_add_u32 v77, v93, 10, v4
	v_lshl_add_u32 v78, v94, 10, v4
	v_lshl_add_u32 v79, v95, 10, v4
	v_lshl_add_u32 v80, v96, 10, v4
	v_lshl_add_u32 v81, v97, 10, v4
	v_lshl_add_u32 v82, v98, 10, v4
	v_lshl_add_u32 v83, v99, 10, v4
	s_add_u32 s18, s60, 0x1100000
	s_addc_u32 s19, s61, 0
	global_load_dwordx4 v[180:183], v4, s[60:61]
	global_load_dwordx4 v[184:187], v4, s[18:19]
	s_add_u32 s14, s58, s20
	s_addc_u32 s15, s59, 0
	global_load_dwordx4 v[84:87], v5, s[14:15] offset:0
	global_load_dwordx4 v[88:91], v5, s[14:15] offset:16
	global_load_dwordx4 v[92:95], v5, s[14:15] offset:32
	global_load_dwordx4 v[96:99], v5, s[14:15] offset:48
	global_load_dwordx4 v[120:123], v68, s[12:13]
	global_load_dwordx4 v[124:127], v69, s[12:13]
	global_load_dwordx4 v[128:131], v70, s[12:13]
	global_load_dwordx4 v[132:135], v71, s[12:13]
	global_load_dwordx4 v[136:139], v72, s[12:13]
	global_load_dwordx4 v[140:143], v73, s[12:13]
	global_load_dwordx4 v[144:147], v74, s[12:13]
	global_load_dwordx4 v[148:151], v75, s[12:13]
	global_load_dwordx4 v[152:155], v76, s[12:13]
	global_load_dwordx4 v[156:159], v77, s[12:13]
	global_load_dwordx4 v[160:163], v78, s[12:13]
	global_load_dwordx4 v[164:167], v79, s[12:13]
	global_load_dwordx4 v[168:171], v80, s[12:13]
	global_load_dwordx4 v[172:175], v81, s[12:13]
	global_load_dwordx4 v[188:191], v82, s[12:13]
	global_load_dwordx4 v[192:195], v83, s[12:13]
	s_mov_b32 s22, 0
;     ...
;     for (int t = 0; t < NTL; ++t) { b0[t] = *(const u32x4_t*)(up[t]); b1[t] = *(const u32x4_t*)(up[t] + 64); }
;     ...
;     for (int m = 0; m < 16; m += 2) {
;         const u32x4_t a0 = *(const u32x4_t*)(hp + m * 64), a1 = *(const u32x4_t*)(hp + m * 64 + 64);
; #pragma unroll
;         for (int t = 0; t < NTL; ++t) FP8MM(a0, b0[t], acc[t]);
;         if (m + 2 < 16) {
; #pragma unroll
;             for (int t = 0; t < NTL; ++t) b0[t] = *(const u32x4_t*)(up[t] + (m + 2) * 64);
;         }
; #pragma unroll
;         for (int t = 0; t < NTL; ++t) FP8MM(a1, b1[t], acc[t]);
;         if (m + 3 < 16) {
; #pragma unroll
;             for (int t = 0; t < NTL; ++t) b1[t] = *(const u32x4_t*)(up[t] + (m + 3) * 64);
;         }
;     }
.Lg1_loop:
	s_waitcnt vmcnt(16)
	v_cvt_pk_f32_fp8_e32 v[10:11], v180
	v_cvt_pk_f32_fp8_sdwa v[12:13], v180 src0_sel:WORD_1
	v_cvt_pk_f32_fp8_e32 v[14:15], v181
	v_cvt_pk_f32_fp8_sdwa v[16:17], v181 src0_sel:WORD_1
	v_cvt_pk_f32_fp8_e32 v[18:19], v182
	v_cvt_pk_f32_fp8_sdwa v[20:21], v182 src0_sel:WORD_1
	v_cvt_pk_f32_fp8_e32 v[22:23], v183
	v_cvt_pk_f32_fp8_sdwa v[24:25], v183 src0_sel:WORD_1
	v_cvt_pk_f32_fp8_e32 v[26:27], v184
	v_cvt_pk_f32_fp8_sdwa v[28:29], v184 src0_sel:WORD_1
	v_cvt_pk_f32_fp8_e32 v[30:31], v185
	v_cvt_pk_f32_fp8_sdwa v[32:33], v185 src0_sel:WORD_1
	v_cvt_pk_f32_fp8_e32 v[34:35], v186
	v_cvt_pk_f32_fp8_sdwa v[36:37], v186 src0_sel:WORD_1
	v_cvt_pk_f32_fp8_e32 v[38:39], v187
	v_cvt_pk_f32_fp8_sdwa v[40:41], v187 src0_sel:WORD_1
	v_pk_fma_f32 v[10:11], v[26:27], v[8:9], v[10:11]
	v_pk_fma_f32 v[12:13], v[28:29], v[8:9], v[12:13]
	v_pk_fma_f32 v[14:15], v[30:31], v[8:9], v[14:15]
	v_pk_fma_f32 v[16:17], v[32:33], v[8:9], v[16:17]
	v_pk_fma_f32 v[18:19], v[34:35], v[8:9], v[18:19]
	v_pk_fma_f32 v[20:21], v[36:37], v[8:9], v[20:21]
	v_pk_fma_f32 v[22:23], v[38:39], v[8:9], v[22:23]
	v_pk_fma_f32 v[24:25], v[40:41], v[8:9], v[24:25]
	v_lshl_add_u32 v68, v84, 10, v4
	v_lshl_add_u32 v69, v85, 10, v4
	v_lshl_add_u32 v70, v86, 10, v4
	v_lshl_add_u32 v71, v87, 10, v4
	v_lshl_add_u32 v72, v88, 10, v4
	v_lshl_add_u32 v73, v89, 10, v4
	v_lshl_add_u32 v74, v90, 10, v4
	v_lshl_add_u32 v75, v91, 10, v4
	v_lshl_add_u32 v76, v92, 10, v4
	v_lshl_add_u32 v77, v93, 10, v4
	v_lshl_add_u32 v78, v94, 10, v4
	v_lshl_add_u32 v79, v95, 10, v4
	v_lshl_add_u32 v80, v96, 10, v4
	v_lshl_add_u32 v81, v97, 10, v4
	v_lshl_add_u32 v82, v98, 10, v4
	v_lshl_add_u32 v83, v99, 10, v4
	s_add_u32 s9, s22, 1
	s_and_b32 s10, s9, 7
	s_lshr_b32 s11, s9, 3
	s_mul_i32 s23, s10, s21
	s_lshl_b32 s11, s11, 7
	s_add_u32 s16, s60, s23
	s_addc_u32 s17, s61, 0
	s_add_u32 s16, s16, s11
	s_addc_u32 s17, s17, 0
	s_add_u32 s18, s16, 0x1100000
	s_addc_u32 s19, s17, 0
	s_add_u32 s12, s56, s11
	s_addc_u32 s13, s57, 0
	s_add_u32 s9, s22, 2
	s_and_b32 s9, s9, 7
	s_mul_i32 s9, s9, s20
	s_add_u32 s14, s58, s9
	s_addc_u32 s15, s59, 0
	global_load_dwordx4 v[180:183], v4, s[16:17]
	global_load_dwordx4 v[184:187], v4, s[18:19]
	global_load_dwordx4 v[84:87], v5, s[14:15] offset:0
	global_load_dwordx4 v[88:91], v5, s[14:15] offset:16
	global_load_dwordx4 v[92:95], v5, s[14:15] offset:32
	global_load_dwordx4 v[96:99], v5, s[14:15] offset:48
	s_waitcnt vmcnt(20)
	v_cvt_pk_f32_fp8_e32 v[26:27], v120
	v_cvt_pk_f32_fp8_sdwa v[28:29], v120 src0_sel:WORD_1
	v_cvt_pk_f32_fp8_e32 v[30:31], v121
	v_cvt_pk_f32_fp8_sdwa v[32:33], v121 src0_sel:WORD_1
	v_cvt_pk_f32_fp8_e32 v[34:35], v122
	v_cvt_pk_f32_fp8_sdwa v[36:37], v122 src0_sel:WORD_1
	v_cvt_pk_f32_fp8_e32 v[38:39], v123
	v_cvt_pk_f32_fp8_sdwa v[40:41], v123 src0_sel:WORD_1
	v_cvt_pk_f32_fp8_e32 v[42:43], v124
	v_cvt_pk_f32_fp8_sdwa v[44:45], v124 src0_sel:WORD_1
	v_cvt_pk_f32_fp8_e32 v[46:47], v125
	v_cvt_pk_f32_fp8_sdwa v[48:49], v125 src0_sel:WORD_1
	v_cvt_pk_f32_fp8_e32 v[50:51], v126
	v_cvt_pk_f32_fp8_sdwa v[52:53], v126 src0_sel:WORD_1
	v_cvt_pk_f32_fp8_e32 v[54:55], v127
	v_cvt_pk_f32_fp8_sdwa v[56:57], v127 src0_sel:WORD_1
	global_load_dwordx4 v[120:123], v68, s[12:13]
	global_load_dwordx4 v[124:127], v69, s[12:13]
	v_pk_mul_f32 v[58:59], v[26:27], v[10:11]
	v_pk_mul_f32 v[60:61], v[42:43], v[10:11]
	v_pk_fma_f32 v[58:59], v[28:29], v[12:13], v[58:59]
	v_pk_fma_f32 v[60:61], v[44:45], v[12:13], v[60:61]
	v_pk_fma_f32 v[58:59], v[30:31], v[14:15], v[58:59]
	v_pk_fma_f32 v[60:61], v[46:47], v[14:15], v[60:61]
	v_pk_fma_f32 v[58:59], v[32:33], v[16:17], v[58:59]
	v_pk_fma_f32 v[60:61], v[48:49], v[16:17], v[60:61]
	v_pk_fma_f32 v[58:59], v[34:35], v[18:19], v[58:59]
	v_pk_fma_f32 v[60:61], v[50:51], v[18:19], v[60:61]
	v_pk_fma_f32 v[58:59], v[36:37], v[20:21], v[58:59]
	v_pk_fma_f32 v[60:61], v[52:53], v[20:21], v[60:61]
	v_pk_fma_f32 v[58:59], v[38:39], v[22:23], v[58:59]
	v_pk_fma_f32 v[60:61], v[54:55], v[22:23], v[60:61]
	v_pk_fma_f32 v[58:59], v[40:41], v[24:25], v[58:59]
	v_pk_fma_f32 v[60:61], v[56:57], v[24:25], v[60:61]
	v_add_f32_e32 v104, v58, v59
	v_add_f32_e32 v105, v60, v61
	s_waitcnt vmcnt(20)
	v_cvt_pk_f32_fp8_e32 v[26:27], v128
	v_cvt_pk_f32_fp8_sdwa v[28:29], v128 src0_sel:WORD_1
	v_cvt_pk_f32_fp8_e32 v[30:31], v129
	v_cvt_pk_f32_fp8_sdwa v[32:33], v129 src0_sel:WORD_1
	v_cvt_pk_f32_fp8_e32 v[34:35], v130
	v_cvt_pk_f32_fp8_sdwa v[36:37], v130 src0_sel:WORD_1
	v_cvt_pk_f32_fp8_e32 v[38:39], v131
	v_cvt_pk_f32_fp8_sdwa v[40:41], v131 src0_sel:WORD_1
	v_cvt_pk_f32_fp8_e32 v[42:43], v132
	v_cvt_pk_f32_fp8_sdwa v[44:45], v132 src0_sel:WORD_1
	v_cvt_pk_f32_fp8_e32 v[46:47], v133
	v_cvt_pk_f32_fp8_sdwa v[48:49], v133 src0_sel:WORD_1
	v_cvt_pk_f32_fp8_e32 v[50:51], v134
	v_cvt_pk_f32_fp8_sdwa v[52:53], v134 src0_sel:WORD_1
	v_cvt_pk_f32_fp8_e32 v[54:55], v135
	v_cvt_pk_f32_fp8_sdwa v[56:57], v135 src0_sel:WORD_1
	global_load_dwordx4 v[128:131], v70, s[12:13]
	global_load_dwordx4 v[132:135], v71, s[12:13]
	v_pk_mul_f32 v[58:59], v[26:27], v[10:11]
	v_pk_mul_f32 v[60:61], v[42:43], v[10:11]
	v_pk_fma_f32 v[58:59], v[28:29], v[12:13], v[58:59]
	v_pk_fma_f32 v[60:61], v[44:45], v[12:13], v[60:61]
	v_pk_fma_f32 v[58:59], v[30:31], v[14:15], v[58:59]
	v_pk_fma_f32 v[60:61], v[46:47], v[14:15], v[60:61]
	v_pk_fma_f32 v[58:59], v[32:33], v[16:17], v[58:59]
	v_pk_fma_f32 v[60:61], v[48:49], v[16:17], v[60:61]
	v_pk_fma_f32 v[58:59], v[34:35], v[18:19], v[58:59]
	v_pk_fma_f32 v[60:61], v[50:51], v[18:19], v[60:61]
	v_pk_fma_f32 v[58:59], v[36:37], v[20:21], v[58:59]
	v_pk_fma_f32 v[60:61], v[52:53], v[20:21], v[60:61]
	v_pk_fma_f32 v[58:59], v[38:39], v[22:23], v[58:59]
	v_pk_fma_f32 v[60:61], v[54:55], v[22:23], v[60:61]
	v_pk_fma_f32 v[58:59], v[40:41], v[24:25], v[58:59]
	v_pk_fma_f32 v[60:61], v[56:57], v[24:25], v[60:61]
	v_add_f32_e32 v106, v58, v59
	v_add_f32_e32 v107, v60, v61
	s_waitcnt vmcnt(20)
;     ...
;     for (int m = 0; m < 16; m += 2) {
;         const u32x4_t a0 = *(const u32x4_t*)(hp + m * 64), a1 = *(const u32x4_t*)(hp + m * 64 + 64);
; #pragma unroll
;         for (int t = 0; t < NTL; ++t) FP8MM(a0, b0[t], acc[t]);
;         if (m + 2 < 16) {
; #pragma unroll
;             for (int t = 0; t < NTL; ++t) b0[t] = *(const u32x4_t*)(up[t] + (m + 2) * 64);
;         }
; #pragma unroll
;         for (int t = 0; t < NTL; ++t) FP8MM(a1, b1[t], acc[t]);
;         if (m + 3 < 16) {
; #pragma unroll
;             for (int t = 0; t < NTL; ++t) b1[t] = *(const u32x4_t*)(up[t] + (m + 3) * 64);
;         }
;     }
	v_cvt_pk_f32_fp8_e32 v[26:27], v136
	v_cvt_pk_f32_fp8_sdwa v[28:29], v136 src0_sel:WORD_1
	v_cvt_pk_f32_fp8_e32 v[30:31], v137
	v_cvt_pk_f32_fp8_sdwa v[32:33], v137 src0_sel:WORD_1
	v_cvt_pk_f32_fp8_e32 v[34:35], v138
	v_cvt_pk_f32_fp8_sdwa v[36:37], v138 src0_sel:WORD_1
	v_cvt_pk_f32_fp8_e32 v[38:39], v139
	v_cvt_pk_f32_fp8_sdwa v[40:41], v139 src0_sel:WORD_1
	v_cvt_pk_f32_fp8_e32 v[42:43], v140
	v_cvt_pk_f32_fp8_sdwa v[44:45], v140 src0_sel:WORD_1
	v_cvt_pk_f32_fp8_e32 v[46:47], v141
	v_cvt_pk_f32_fp8_sdwa v[48:49], v141 src0_sel:WORD_1
	v_cvt_pk_f32_fp8_e32 v[50:51], v142
	v_cvt_pk_f32_fp8_sdwa v[52:53], v142 src0_sel:WORD_1
	v_cvt_pk_f32_fp8_e32 v[54:55], v143
	v_cvt_pk_f32_fp8_sdwa v[56:57], v143 src0_sel:WORD_1
	global_load_dwordx4 v[136:139], v72, s[12:13]
	global_load_dwordx4 v[140:143], v73, s[12:13]
	v_pk_mul_f32 v[58:59], v[26:27], v[10:11]
	v_pk_mul_f32 v[60:61], v[42:43], v[10:11]
	v_pk_fma_f32 v[58:59], v[28:29], v[12:13], v[58:59]
	v_pk_fma_f32 v[60:61], v[44:45], v[12:13], v[60:61]
	v_pk_fma_f32 v[58:59], v[30:31], v[14:15], v[58:59]
	v_pk_fma_f32 v[60:61], v[46:47], v[14:15], v[60:61]
	v_pk_fma_f32 v[58:59], v[32:33], v[16:17], v[58:59]
	v_pk_fma_f32 v[60:61], v[48:49], v[16:17], v[60:61]
	v_pk_fma_f32 v[58:59], v[34:35], v[18:19], v[58:59]
	v_pk_fma_f32 v[60:61], v[50:51], v[18:19], v[60:61]
	v_pk_fma_f32 v[58:59], v[36:37], v[20:21], v[58:59]
	v_pk_fma_f32 v[60:61], v[52:53], v[20:21], v[60:61]
	v_pk_fma_f32 v[58:59], v[38:39], v[22:23], v[58:59]
	v_pk_fma_f32 v[60:61], v[54:55], v[22:23], v[60:61]
	v_pk_fma_f32 v[58:59], v[40:41], v[24:25], v[58:59]
	v_pk_fma_f32 v[60:61], v[56:57], v[24:25], v[60:61]
	v_add_f32_e32 v108, v58, v59
	v_add_f32_e32 v109, v60, v61
	s_waitcnt vmcnt(20)
	v_cvt_pk_f32_fp8_e32 v[26:27], v144
	v_cvt_pk_f32_fp8_sdwa v[28:29], v144 src0_sel:WORD_1
	v_cvt_pk_f32_fp8_e32 v[30:31], v145
	v_cvt_pk_f32_fp8_sdwa v[32:33], v145 src0_sel:WORD_1
	v_cvt_pk_f32_fp8_e32 v[34:35], v146
	v_cvt_pk_f32_fp8_sdwa v[36:37], v146 src0_sel:WORD_1
	v_cvt_pk_f32_fp8_e32 v[38:39], v147
	v_cvt_pk_f32_fp8_sdwa v[40:41], v147 src0_sel:WORD_1
	v_cvt_pk_f32_fp8_e32 v[42:43], v148
	v_cvt_pk_f32_fp8_sdwa v[44:45], v148 src0_sel:WORD_1
	v_cvt_pk_f32_fp8_e32 v[46:47], v149
	v_cvt_pk_f32_fp8_sdwa v[48:49], v149 src0_sel:WORD_1
	v_cvt_pk_f32_fp8_e32 v[50:51], v150
	v_cvt_pk_f32_fp8_sdwa v[52:53], v150 src0_sel:WORD_1
	v_cvt_pk_f32_fp8_e32 v[54:55], v151
	v_cvt_pk_f32_fp8_sdwa v[56:57], v151 src0_sel:WORD_1
	global_load_dwordx4 v[144:147], v74, s[12:13]
	global_load_dwordx4 v[148:151], v75, s[12:13]
	v_pk_mul_f32 v[58:59], v[26:27], v[10:11]
	v_pk_mul_f32 v[60:61], v[42:43], v[10:11]
	v_pk_fma_f32 v[58:59], v[28:29], v[12:13], v[58:59]
	v_pk_fma_f32 v[60:61], v[44:45], v[12:13], v[60:61]
	v_pk_fma_f32 v[58:59], v[30:31], v[14:15], v[58:59]
	v_pk_fma_f32 v[60:61], v[46:47], v[14:15], v[60:61]
	v_pk_fma_f32 v[58:59], v[32:33], v[16:17], v[58:59]
	v_pk_fma_f32 v[60:61], v[48:49], v[16:17], v[60:61]
	v_pk_fma_f32 v[58:59], v[34:35], v[18:19], v[58:59]
	v_pk_fma_f32 v[60:61], v[50:51], v[18:19], v[60:61]
	v_pk_fma_f32 v[58:59], v[36:37], v[20:21], v[58:59]
	v_pk_fma_f32 v[60:61], v[52:53], v[20:21], v[60:61]
	v_pk_fma_f32 v[58:59], v[38:39], v[22:23], v[58:59]
	v_pk_fma_f32 v[60:61], v[54:55], v[22:23], v[60:61]
	v_pk_fma_f32 v[58:59], v[40:41], v[24:25], v[58:59]
	v_pk_fma_f32 v[60:61], v[56:57], v[24:25], v[60:61]
	v_add_f32_e32 v110, v58, v59
	v_add_f32_e32 v111, v60, v61
	s_waitcnt vmcnt(20)
	v_cvt_pk_f32_fp8_e32 v[26:27], v152
	v_cvt_pk_f32_fp8_sdwa v[28:29], v152 src0_sel:WORD_1
	v_cvt_pk_f32_fp8_e32 v[30:31], v153
	v_cvt_pk_f32_fp8_sdwa v[32:33], v153 src0_sel:WORD_1
	v_cvt_pk_f32_fp8_e32 v[34:35], v154
	v_cvt_pk_f32_fp8_sdwa v[36:37], v154 src0_sel:WORD_1
	v_cvt_pk_f32_fp8_e32 v[38:39], v155
	v_cvt_pk_f32_fp8_sdwa v[40:41], v155 src0_sel:WORD_1
	v_cvt_pk_f32_fp8_e32 v[42:43], v156
	v_cvt_pk_f32_fp8_sdwa v[44:45], v156 src0_sel:WORD_1
	v_cvt_pk_f32_fp8_e32 v[46:47], v157
	v_cvt_pk_f32_fp8_sdwa v[48:49], v157 src0_sel:WORD_1
	v_cvt_pk_f32_fp8_e32 v[50:51], v158
	v_cvt_pk_f32_fp8_sdwa v[52:53], v158 src0_sel:WORD_1
	v_cvt_pk_f32_fp8_e32 v[54:55], v159
	v_cvt_pk_f32_fp8_sdwa v[56:57], v159 src0_sel:WORD_1
	global_load_dwordx4 v[152:155], v76, s[12:13]
	global_load_dwordx4 v[156:159], v77, s[12:13]
	v_pk_mul_f32 v[58:59], v[26:27], v[10:11]
	v_pk_mul_f32 v[60:61], v[42:43], v[10:11]
	v_pk_fma_f32 v[58:59], v[28:29], v[12:13], v[58:59]
	v_pk_fma_f32 v[60:61], v[44:45], v[12:13], v[60:61]
	v_pk_fma_f32 v[58:59], v[30:31], v[14:15], v[58:59]
	v_pk_fma_f32 v[60:61], v[46:47], v[14:15], v[60:61]
	v_pk_fma_f32 v[58:59], v[32:33], v[16:17], v[58:59]
	v_pk_fma_f32 v[60:61], v[48:49], v[16:17], v[60:61]
	v_pk_fma_f32 v[58:59], v[34:35], v[18:19], v[58:59]
	v_pk_fma_f32 v[60:61], v[50:51], v[18:19], v[60:61]
	v_pk_fma_f32 v[58:59], v[36:37], v[20:21], v[58:59]
	v_pk_fma_f32 v[60:61], v[52:53], v[20:21], v[60:61]
	v_pk_fma_f32 v[58:59], v[38:39], v[22:23], v[58:59]
	v_pk_fma_f32 v[60:61], v[54:55], v[22:23], v[60:61]
	v_pk_fma_f32 v[58:59], v[40:41], v[24:25], v[58:59]
	v_pk_fma_f32 v[60:61], v[56:57], v[24:25], v[60:61]
	v_add_f32_e32 v112, v58, v59
	v_add_f32_e32 v113, v60, v61
	s_waitcnt vmcnt(20)
; DEVI float gelu_f(float x) { const float u = 0.7978845608028654f * (x + 0.044715f * x * x * x); return x * __builtin_amdgcn_rcpf(1.f + __expf(-2.f * u)); }
;     ...
;     for (int m = 0; m < 16; m += 2) {
;         const u32x4_t a0 = *(const u32x4_t*)(hp + m * 64), a1 = *(const u32x4_t*)(hp + m * 64 + 64);
; #pragma unroll
;         for (int t = 0; t < NTL; ++t) FP8MM(a0, b0[t], acc[t]);
;         if (m + 2 < 16) {
; #pragma unroll
;             for (int t = 0; t < NTL; ++t) b0[t] = *(const u32x4_t*)(up[t] + (m + 2) * 64);
;         }
; #pragma unroll
;         for (int t = 0; t < NTL; ++t) FP8MM(a1, b1[t], acc[t]);
;         if (m + 3 < 16) {
; #pragma unroll
;             for (int t = 0; t < NTL; ++t) b1[t] = *(const u32x4_t*)(up[t] + (m + 3) * 64);
;         }
;     }
;     ...
; #pragma unroll
;     for (int t = 0; t < NTL; ++t) { const float lo = __shfl_xor(acc[t][0], 32); const float dot = (acc[t][0] + lo * (1.f / 32.f)) * s_u[t];
;         if (kq == 0) pl[t * 16 + n16] = (u32x2_t){(unsigned)e[t], __float_as_uint(g[t] * gelu_f(dot) * s_v[t])}; }
	v_cvt_pk_f32_fp8_e32 v[26:27], v160
	v_cvt_pk_f32_fp8_sdwa v[28:29], v160 src0_sel:WORD_1
	v_cvt_pk_f32_fp8_e32 v[30:31], v161
	v_cvt_pk_f32_fp8_sdwa v[32:33], v161 src0_sel:WORD_1
	v_cvt_pk_f32_fp8_e32 v[34:35], v162
	v_cvt_pk_f32_fp8_sdwa v[36:37], v162 src0_sel:WORD_1
	v_cvt_pk_f32_fp8_e32 v[38:39], v163
	v_cvt_pk_f32_fp8_sdwa v[40:41], v163 src0_sel:WORD_1
	v_cvt_pk_f32_fp8_e32 v[42:43], v164
	v_cvt_pk_f32_fp8_sdwa v[44:45], v164 src0_sel:WORD_1
	v_cvt_pk_f32_fp8_e32 v[46:47], v165
	v_cvt_pk_f32_fp8_sdwa v[48:49], v165 src0_sel:WORD_1
	v_cvt_pk_f32_fp8_e32 v[50:51], v166
	v_cvt_pk_f32_fp8_sdwa v[52:53], v166 src0_sel:WORD_1
	v_cvt_pk_f32_fp8_e32 v[54:55], v167
	v_cvt_pk_f32_fp8_sdwa v[56:57], v167 src0_sel:WORD_1
	global_load_dwordx4 v[160:163], v78, s[12:13]
	global_load_dwordx4 v[164:167], v79, s[12:13]
	v_pk_mul_f32 v[58:59], v[26:27], v[10:11]
	v_pk_mul_f32 v[60:61], v[42:43], v[10:11]
	v_pk_fma_f32 v[58:59], v[28:29], v[12:13], v[58:59]
	v_pk_fma_f32 v[60:61], v[44:45], v[12:13], v[60:61]
	v_pk_fma_f32 v[58:59], v[30:31], v[14:15], v[58:59]
	v_pk_fma_f32 v[60:61], v[46:47], v[14:15], v[60:61]
	v_pk_fma_f32 v[58:59], v[32:33], v[16:17], v[58:59]
	v_pk_fma_f32 v[60:61], v[48:49], v[16:17], v[60:61]
	v_pk_fma_f32 v[58:59], v[34:35], v[18:19], v[58:59]
	v_pk_fma_f32 v[60:61], v[50:51], v[18:19], v[60:61]
	v_pk_fma_f32 v[58:59], v[36:37], v[20:21], v[58:59]
	v_pk_fma_f32 v[60:61], v[52:53], v[20:21], v[60:61]
	v_pk_fma_f32 v[58:59], v[38:39], v[22:23], v[58:59]
	v_pk_fma_f32 v[60:61], v[54:55], v[22:23], v[60:61]
	v_pk_fma_f32 v[58:59], v[40:41], v[24:25], v[58:59]
	v_pk_fma_f32 v[60:61], v[56:57], v[24:25], v[60:61]
	v_add_f32_e32 v114, v58, v59
	v_add_f32_e32 v115, v60, v61
	s_waitcnt vmcnt(20)
	v_cvt_pk_f32_fp8_e32 v[26:27], v168
	v_cvt_pk_f32_fp8_sdwa v[28:29], v168 src0_sel:WORD_1
	v_cvt_pk_f32_fp8_e32 v[30:31], v169
	v_cvt_pk_f32_fp8_sdwa v[32:33], v169 src0_sel:WORD_1
	v_cvt_pk_f32_fp8_e32 v[34:35], v170
	v_cvt_pk_f32_fp8_sdwa v[36:37], v170 src0_sel:WORD_1
	v_cvt_pk_f32_fp8_e32 v[38:39], v171
	v_cvt_pk_f32_fp8_sdwa v[40:41], v171 src0_sel:WORD_1
	v_cvt_pk_f32_fp8_e32 v[42:43], v172
	v_cvt_pk_f32_fp8_sdwa v[44:45], v172 src0_sel:WORD_1
	v_cvt_pk_f32_fp8_e32 v[46:47], v173
	v_cvt_pk_f32_fp8_sdwa v[48:49], v173 src0_sel:WORD_1
	v_cvt_pk_f32_fp8_e32 v[50:51], v174
	v_cvt_pk_f32_fp8_sdwa v[52:53], v174 src0_sel:WORD_1
	v_cvt_pk_f32_fp8_e32 v[54:55], v175
	v_cvt_pk_f32_fp8_sdwa v[56:57], v175 src0_sel:WORD_1
	global_load_dwordx4 v[168:171], v80, s[12:13]
	global_load_dwordx4 v[172:175], v81, s[12:13]
	v_pk_mul_f32 v[58:59], v[26:27], v[10:11]
	v_pk_mul_f32 v[60:61], v[42:43], v[10:11]
	v_pk_fma_f32 v[58:59], v[28:29], v[12:13], v[58:59]
	v_pk_fma_f32 v[60:61], v[44:45], v[12:13], v[60:61]
	v_pk_fma_f32 v[58:59], v[30:31], v[14:15], v[58:59]
	v_pk_fma_f32 v[60:61], v[46:47], v[14:15], v[60:61]
	v_pk_fma_f32 v[58:59], v[32:33], v[16:17], v[58:59]
	v_pk_fma_f32 v[60:61], v[48:49], v[16:17], v[60:61]
	v_pk_fma_f32 v[58:59], v[34:35], v[18:19], v[58:59]
	v_pk_fma_f32 v[60:61], v[50:51], v[18:19], v[60:61]
	v_pk_fma_f32 v[58:59], v[36:37], v[20:21], v[58:59]
	v_pk_fma_f32 v[60:61], v[52:53], v[20:21], v[60:61]
	v_pk_fma_f32 v[58:59], v[38:39], v[22:23], v[58:59]
	v_pk_fma_f32 v[60:61], v[54:55], v[22:23], v[60:61]
	v_pk_fma_f32 v[58:59], v[40:41], v[24:25], v[58:59]
	v_pk_fma_f32 v[60:61], v[56:57], v[24:25], v[60:61]
	v_add_f32_e32 v62, v58, v59
	v_add_f32_e32 v63, v60, v61
	s_waitcnt vmcnt(20)
	v_cvt_pk_f32_fp8_e32 v[26:27], v188
	v_cvt_pk_f32_fp8_sdwa v[28:29], v188 src0_sel:WORD_1
	v_cvt_pk_f32_fp8_e32 v[30:31], v189
	v_cvt_pk_f32_fp8_sdwa v[32:33], v189 src0_sel:WORD_1
	v_cvt_pk_f32_fp8_e32 v[34:35], v190
	v_cvt_pk_f32_fp8_sdwa v[36:37], v190 src0_sel:WORD_1
	v_cvt_pk_f32_fp8_e32 v[38:39], v191
	v_cvt_pk_f32_fp8_sdwa v[40:41], v191 src0_sel:WORD_1
	v_cvt_pk_f32_fp8_e32 v[42:43], v192
	v_cvt_pk_f32_fp8_sdwa v[44:45], v192 src0_sel:WORD_1
	v_cvt_pk_f32_fp8_e32 v[46:47], v193
	v_cvt_pk_f32_fp8_sdwa v[48:49], v193 src0_sel:WORD_1
	v_cvt_pk_f32_fp8_e32 v[50:51], v194
	v_cvt_pk_f32_fp8_sdwa v[52:53], v194 src0_sel:WORD_1
	v_cvt_pk_f32_fp8_e32 v[54:55], v195
	v_cvt_pk_f32_fp8_sdwa v[56:57], v195 src0_sel:WORD_1
	global_load_dwordx4 v[188:191], v82, s[12:13]
	global_load_dwordx4 v[192:195], v83, s[12:13]
	v_pk_mul_f32 v[58:59], v[26:27], v[10:11]
	v_pk_mul_f32 v[60:61], v[42:43], v[10:11]
	v_pk_fma_f32 v[58:59], v[28:29], v[12:13], v[58:59]
	v_pk_fma_f32 v[60:61], v[44:45], v[12:13], v[60:61]
	v_pk_fma_f32 v[58:59], v[30:31], v[14:15], v[58:59]
	v_pk_fma_f32 v[60:61], v[46:47], v[14:15], v[60:61]
	v_pk_fma_f32 v[58:59], v[32:33], v[16:17], v[58:59]
	v_pk_fma_f32 v[60:61], v[48:49], v[16:17], v[60:61]
	v_pk_fma_f32 v[58:59], v[34:35], v[18:19], v[58:59]
	v_pk_fma_f32 v[60:61], v[50:51], v[18:19], v[60:61]
	v_pk_fma_f32 v[58:59], v[36:37], v[20:21], v[58:59]
	v_pk_fma_f32 v[60:61], v[52:53], v[20:21], v[60:61]
	v_pk_fma_f32 v[58:59], v[38:39], v[22:23], v[58:59]
	v_pk_fma_f32 v[60:61], v[54:55], v[22:23], v[60:61]
	v_pk_fma_f32 v[58:59], v[40:41], v[24:25], v[58:59]
	v_pk_fma_f32 v[60:61], v[56:57], v[24:25], v[60:61]
	v_add_f32_e32 v64, v58, v59
	v_add_f32_e32 v65, v60, v61
	s_nop 1
	v_add_f32_dpp v104, v104, v104 quad_perm:[1,0,3,2] row_mask:0xf bank_mask:0xf
	v_add_f32_dpp v105, v105, v105 quad_perm:[1,0,3,2] row_mask:0xf bank_mask:0xf
	v_add_f32_dpp v106, v106, v106 quad_perm:[1,0,3,2] row_mask:0xf bank_mask:0xf
	v_add_f32_dpp v107, v107, v107 quad_perm:[1,0,3,2] row_mask:0xf bank_mask:0xf
	v_add_f32_dpp v108, v108, v108 quad_perm:[1,0,3,2] row_mask:0xf bank_mask:0xf
	v_add_f32_dpp v109, v109, v109 quad_perm:[1,0,3,2] row_mask:0xf bank_mask:0xf
;     DEVI int* eidx() const { return (int*)(ws + WS_EIDX); }
; DEVI float gelu_f(float x) { const float u = 0.7978845608028654f * (x + 0.044715f * x * x * x); return x * __builtin_amdgcn_rcpf(1.f + __expf(-2.f * u)); }
;     ...
;     int e[NTL]; float g[NTL], s_u[NTL], s_v[NTL];
; #pragma unroll
;     for (int t = 0; t < NTL; ++t) { e[t] = eidx[(size_t)r * 128 + (tbase + t) * 16 + n16]; g[t] = gwv[(size_t)r * 128 + (tbase + t) * 16 + n16]; }
; #pragma unroll
;     for (int t = 0; t < NTL; ++t) { s_u[t] = su[e[t]]; s_v[t] = sv[e[t]]; }
;     ...
;     for (int t = 0; t < NTL; ++t) { const float lo = __shfl_xor(acc[t][0], 32); const float dot = (acc[t][0] + lo * (1.f / 32.f)) * s_u[t];
;         if (kq == 0) pl[t * 16 + n16] = (u32x2_t){(unsigned)e[t], __float_as_uint(g[t] * gelu_f(dot) * s_v[t])}; }
	v_add_f32_dpp v110, v110, v110 quad_perm:[1,0,3,2] row_mask:0xf bank_mask:0xf
	v_add_f32_dpp v111, v111, v111 quad_perm:[1,0,3,2] row_mask:0xf bank_mask:0xf
	v_add_f32_dpp v112, v112, v112 quad_perm:[1,0,3,2] row_mask:0xf bank_mask:0xf
	v_add_f32_dpp v113, v113, v113 quad_perm:[1,0,3,2] row_mask:0xf bank_mask:0xf
	v_add_f32_dpp v114, v114, v114 quad_perm:[1,0,3,2] row_mask:0xf bank_mask:0xf
	v_add_f32_dpp v115, v115, v115 quad_perm:[1,0,3,2] row_mask:0xf bank_mask:0xf
	v_add_f32_dpp v62, v62, v62 quad_perm:[1,0,3,2] row_mask:0xf bank_mask:0xf
	v_add_f32_dpp v63, v63, v63 quad_perm:[1,0,3,2] row_mask:0xf bank_mask:0xf
	v_add_f32_dpp v64, v64, v64 quad_perm:[1,0,3,2] row_mask:0xf bank_mask:0xf
	v_add_f32_dpp v65, v65, v65 quad_perm:[1,0,3,2] row_mask:0xf bank_mask:0xf
	v_add_f32_dpp v104, v104, v104 quad_perm:[2,3,0,1] row_mask:0xf bank_mask:0xf
	v_add_f32_dpp v105, v105, v105 quad_perm:[2,3,0,1] row_mask:0xf bank_mask:0xf
	v_add_f32_dpp v106, v106, v106 quad_perm:[2,3,0,1] row_mask:0xf bank_mask:0xf
	v_add_f32_dpp v107, v107, v107 quad_perm:[2,3,0,1] row_mask:0xf bank_mask:0xf
	v_add_f32_dpp v108, v108, v108 quad_perm:[2,3,0,1] row_mask:0xf bank_mask:0xf
	v_add_f32_dpp v109, v109, v109 quad_perm:[2,3,0,1] row_mask:0xf bank_mask:0xf
	v_add_f32_dpp v110, v110, v110 quad_perm:[2,3,0,1] row_mask:0xf bank_mask:0xf
	v_add_f32_dpp v111, v111, v111 quad_perm:[2,3,0,1] row_mask:0xf bank_mask:0xf
	v_add_f32_dpp v112, v112, v112 quad_perm:[2,3,0,1] row_mask:0xf bank_mask:0xf
	v_add_f32_dpp v113, v113, v113 quad_perm:[2,3,0,1] row_mask:0xf bank_mask:0xf
	v_add_f32_dpp v114, v114, v114 quad_perm:[2,3,0,1] row_mask:0xf bank_mask:0xf
	v_add_f32_dpp v115, v115, v115 quad_perm:[2,3,0,1] row_mask:0xf bank_mask:0xf
	v_add_f32_dpp v62, v62, v62 quad_perm:[2,3,0,1] row_mask:0xf bank_mask:0xf
	v_add_f32_dpp v63, v63, v63 quad_perm:[2,3,0,1] row_mask:0xf bank_mask:0xf
	v_add_f32_dpp v64, v64, v64 quad_perm:[2,3,0,1] row_mask:0xf bank_mask:0xf
	v_add_f32_dpp v65, v65, v65 quad_perm:[2,3,0,1] row_mask:0xf bank_mask:0xf
	v_add_f32_dpp v104, v104, v104 row_half_mirror row_mask:0xf bank_mask:0xf
	v_add_f32_dpp v105, v105, v105 row_half_mirror row_mask:0xf bank_mask:0xf
	v_add_f32_dpp v106, v106, v106 row_half_mirror row_mask:0xf bank_mask:0xf
	v_add_f32_dpp v107, v107, v107 row_half_mirror row_mask:0xf bank_mask:0xf
	v_add_f32_dpp v108, v108, v108 row_half_mirror row_mask:0xf bank_mask:0xf
	v_add_f32_dpp v109, v109, v109 row_half_mirror row_mask:0xf bank_mask:0xf
	v_add_f32_dpp v110, v110, v110 row_half_mirror row_mask:0xf bank_mask:0xf
	v_add_f32_dpp v111, v111, v111 row_half_mirror row_mask:0xf bank_mask:0xf
	v_add_f32_dpp v112, v112, v112 row_half_mirror row_mask:0xf bank_mask:0xf
	v_add_f32_dpp v113, v113, v113 row_half_mirror row_mask:0xf bank_mask:0xf
	v_add_f32_dpp v114, v114, v114 row_half_mirror row_mask:0xf bank_mask:0xf
	v_add_f32_dpp v115, v115, v115 row_half_mirror row_mask:0xf bank_mask:0xf
	v_add_f32_dpp v62, v62, v62 row_half_mirror row_mask:0xf bank_mask:0xf
	v_add_f32_dpp v63, v63, v63 row_half_mirror row_mask:0xf bank_mask:0xf
	v_add_f32_dpp v64, v64, v64 row_half_mirror row_mask:0xf bank_mask:0xf
	v_add_f32_dpp v65, v65, v65 row_half_mirror row_mask:0xf bank_mask:0xf
	v_cndmask_b32_e64 v118, v118, v104, s[24:25]
	v_cndmask_b32_e64 v119, v119, v105, s[24:25]
	v_cndmask_b32_e64 v118, v118, v106, s[26:27]
	v_cndmask_b32_e64 v119, v119, v107, s[26:27]
	v_cndmask_b32_e64 v118, v118, v108, s[28:29]
	v_cndmask_b32_e64 v119, v119, v109, s[28:29]
	v_cndmask_b32_e64 v118, v118, v110, s[30:31]
	v_cndmask_b32_e64 v119, v119, v111, s[30:31]
	v_cndmask_b32_e64 v118, v118, v112, s[40:41]
	v_cndmask_b32_e64 v119, v119, v113, s[40:41]
	v_cndmask_b32_e64 v118, v118, v114, s[42:43]
	v_cndmask_b32_e64 v119, v119, v115, s[42:43]
	v_cndmask_b32_e64 v118, v118, v62, s[44:45]
	v_cndmask_b32_e64 v119, v119, v63, s[44:45]
	v_cndmask_b32_e64 v118, v118, v64, s[54:55]
	v_cndmask_b32_e64 v119, v119, v65, s[54:55]
	s_and_b32 s9, s22, 7
	s_lshl_b32 s9, s9, 10
	v_add_u32_e32 v7, s9, v6
	ds_add_f32 v7, v118 offset:4
	ds_add_f32 v7, v119 offset:12
	s_add_u32 s22, s22, 1
	s_cmp_lg_u32 s22, 64
	s_cbranch_scc1 .Lg1_loop
	s_waitcnt vmcnt(0) lgkmcnt(0)
	s_lshl_b32 s9, s48, 9
	s_lshl_b32 s20, s34, 9
	s_add_u32 s10, s6, 0x1b292100
	s_addc_u32 s11, s7, 0
	s_add_u32 s10, s10, s9
	s_addc_u32 s11, s11, 0
	s_add_u32 s12, s6, 0x1bb12100
	s_addc_u32 s13, s7, 0
	s_add_u32 s12, s12, s9
	s_addc_u32 s13, s13, 0
	s_lshl_b32 s9, s8, 16
	s_add_u32 s16, s6, 0x2fa42100
	s_addc_u32 s17, s7, 0
	s_add_u32 s16, s16, s9
	s_addc_u32 s17, s17, 0
	s_add_u32 s18, s16, 0x40000
	s_addc_u32 s19, s17, 0
	v_lshlrev_b32_e32 v2, 3, v1
	v_lshl_add_u32 v3, v1, 4, s85
	ds_read_b128 v[68:71], v3 offset:0
	ds_read_b128 v[72:75], v3 offset:1024
	ds_read_b128 v[76:79], v3 offset:2048
	ds_read_b128 v[80:83], v3 offset:3072
	ds_read_b128 v[84:87], v3 offset:4096
	ds_read_b128 v[88:91], v3 offset:5120
	ds_read_b128 v[92:95], v3 offset:6144
	ds_read_b128 v[96:99], v3 offset:7168
	global_load_dwordx2 v[20:21], v2, s[10:11]
	global_load_dwordx2 v[22:23], v2, s[12:13]
	s_add_u32 s10, s10, s20
	s_addc_u32 s11, s11, 0
	s_add_u32 s12, s12, s20
	s_addc_u32 s13, s13, 0
	global_load_dwordx2 v[24:25], v2, s[10:11]
	global_load_dwordx2 v[26:27], v2, s[12:13]
	s_add_u32 s10, s10, s20
	s_addc_u32 s11, s11, 0
	s_add_u32 s12, s12, s20
	s_addc_u32 s13, s13, 0
	global_load_dwordx2 v[28:29], v2, s[10:11]
	global_load_dwordx2 v[30:31], v2, s[12:13]
	s_add_u32 s10, s10, s20
	s_addc_u32 s11, s11, 0
	s_add_u32 s12, s12, s20
	s_addc_u32 s13, s13, 0
	global_load_dwordx2 v[32:33], v2, s[10:11]
	global_load_dwordx2 v[34:35], v2, s[12:13]
	s_add_u32 s10, s10, s20
	s_addc_u32 s11, s11, 0
	s_add_u32 s12, s12, s20
	s_addc_u32 s13, s13, 0
	global_load_dwordx2 v[36:37], v2, s[10:11]
	global_load_dwordx2 v[38:39], v2, s[12:13]
	s_add_u32 s10, s10, s20
	s_addc_u32 s11, s11, 0
	s_add_u32 s12, s12, s20
	s_addc_u32 s13, s13, 0
	global_load_dwordx2 v[40:41], v2, s[10:11]
	global_load_dwordx2 v[42:43], v2, s[12:13]
	s_add_u32 s10, s10, s20
	s_addc_u32 s11, s11, 0
	s_add_u32 s12, s12, s20
	s_addc_u32 s13, s13, 0
	global_load_dwordx2 v[44:45], v2, s[10:11]
	global_load_dwordx2 v[46:47], v2, s[12:13]
	s_add_u32 s10, s10, s20
	s_addc_u32 s11, s11, 0
	s_add_u32 s12, s12, s20
	s_addc_u32 s13, s13, 0
	global_load_dwordx2 v[48:49], v2, s[10:11]
	global_load_dwordx2 v[50:51], v2, s[12:13]
	s_add_u32 s10, s10, s20
	s_addc_u32 s11, s11, 0
	s_add_u32 s12, s12, s20
	s_addc_u32 s13, s13, 0
	s_waitcnt vmcnt(15)
;     DEVI int* eidx() const { return (int*)(ws + WS_EIDX); }
; DEVI float gelu_f(float x) { const float u = 0.7978845608028654f * (x + 0.044715f * x * x * x); return x * __builtin_amdgcn_rcpf(1.f + __expf(-2.f * u)); }
;     ...
;     for (int t = 0; t < NTL; ++t) { e[t] = eidx[(size_t)r * 128 + (tbase + t) * 16 + n16]; g[t] = gwv[(size_t)r * 128 + (tbase + t) * 16 + n16]; }
; #pragma unroll
;     for (int t = 0; t < NTL; ++t) { s_u[t] = su[e[t]]; s_v[t] = sv[e[t]]; }
;     ...
;     for (int t = 0; t < NTL; ++t) { const float lo = __shfl_xor(acc[t][0], 32); const float dot = (acc[t][0] + lo * (1.f / 32.f)) * s_u[t];
;         if (kq == 0) pl[t * 16 + n16] = (u32x2_t){(unsigned)e[t], __float_as_uint(g[t] * gelu_f(dot) * s_v[t])}; }
	v_lshlrev_b32_e32 v4, 2, v20
	v_lshlrev_b32_e32 v5, 2, v21
	global_load_dword v120, v4, s[16:17]
	global_load_dword v121, v5, s[16:17]
	global_load_dword v122, v4, s[18:19]
	global_load_dword v123, v5, s[18:19]
	s_waitcnt vmcnt(17)
	v_lshlrev_b32_e32 v4, 2, v24
	v_lshlrev_b32_e32 v5, 2, v25
	global_load_dword v124, v4, s[16:17]
	global_load_dword v125, v5, s[16:17]
	global_load_dword v126, v4, s[18:19]
	global_load_dword v127, v5, s[18:19]
	s_waitcnt vmcnt(19)
	v_lshlrev_b32_e32 v4, 2, v28
	v_lshlrev_b32_e32 v5, 2, v29
	global_load_dword v128, v4, s[16:17]
	global_load_dword v129, v5, s[16:17]
	global_load_dword v130, v4, s[18:19]
	global_load_dword v131, v5, s[18:19]
	s_waitcnt vmcnt(21)
	v_lshlrev_b32_e32 v4, 2, v32
	v_lshlrev_b32_e32 v5, 2, v33
	global_load_dword v132, v4, s[16:17]
	global_load_dword v133, v5, s[16:17]
	global_load_dword v134, v4, s[18:19]
	global_load_dword v135, v5, s[18:19]
	s_waitcnt vmcnt(23)
	v_lshlrev_b32_e32 v4, 2, v36
	v_lshlrev_b32_e32 v5, 2, v37
	global_load_dword v136, v4, s[16:17]
	global_load_dword v137, v5, s[16:17]
	global_load_dword v138, v4, s[18:19]
	global_load_dword v139, v5, s[18:19]
	s_waitcnt vmcnt(25)
	v_lshlrev_b32_e32 v4, 2, v40
	v_lshlrev_b32_e32 v5, 2, v41
	global_load_dword v140, v4, s[16:17]
	global_load_dword v141, v5, s[16:17]
	global_load_dword v142, v4, s[18:19]
	global_load_dword v143, v5, s[18:19]
	s_waitcnt vmcnt(27)
	v_lshlrev_b32_e32 v4, 2, v44
	v_lshlrev_b32_e32 v5, 2, v45
	global_load_dword v144, v4, s[16:17]
	global_load_dword v145, v5, s[16:17]
	global_load_dword v146, v4, s[18:19]
	global_load_dword v147, v5, s[18:19]
	s_waitcnt vmcnt(29)
	v_lshlrev_b32_e32 v4, 2, v48
	v_lshlrev_b32_e32 v5, 2, v49
	global_load_dword v148, v4, s[16:17]
	global_load_dword v149, v5, s[16:17]
	global_load_dword v150, v4, s[18:19]
	global_load_dword v151, v5, s[18:19]
	s_waitcnt lgkmcnt(0)
	s_waitcnt vmcnt(28)
	v_mul_f32_e32 v69, v69, v120
	v_mul_f32_e32 v6, 0x3d372713, v69
	v_mul_f32_e32 v6, v69, v6
	v_fma_f32 v6, v69, v6, v69
	v_mul_f32_e32 v6, 0x3f4c422a, v6
	v_mul_f32_e32 v6, -2.0, v6
	v_mul_f32_e32 v6, 0x3fb8aa3b, v6
	v_exp_f32_e32 v6, v6
	s_nop 0
	v_add_f32_e32 v6, 1.0, v6
	v_rcp_f32_e32 v6, v6
	s_nop 0
	v_mul_f32_e32 v69, v69, v6
	v_mul_f32_e32 v69, v22, v69
	v_mul_f32_e32 v69, v122, v69
	v_mul_f32_e32 v71, v71, v121
	v_mul_f32_e32 v7, 0x3d372713, v71
	v_mul_f32_e32 v7, v71, v7
	v_fma_f32 v7, v71, v7, v71
	v_mul_f32_e32 v7, 0x3f4c422a, v7
	v_mul_f32_e32 v7, -2.0, v7
	v_mul_f32_e32 v7, 0x3fb8aa3b, v7
	v_exp_f32_e32 v7, v7
	s_nop 0
	v_add_f32_e32 v7, 1.0, v7
	v_rcp_f32_e32 v7, v7
	s_nop 0
	v_mul_f32_e32 v71, v71, v7
	v_mul_f32_e32 v71, v23, v71
	v_mul_f32_e32 v71, v123, v71
	v_mov_b32_e32 v68, v20
	v_mov_b32_e32 v70, v21
	ds_write_b128 v3, v[68:71] offset:0
	s_waitcnt vmcnt(24)
	v_mul_f32_e32 v73, v73, v124
	v_mul_f32_e32 v6, 0x3d372713, v73
	v_mul_f32_e32 v6, v73, v6
	v_fma_f32 v6, v73, v6, v73
	v_mul_f32_e32 v6, 0x3f4c422a, v6
	v_mul_f32_e32 v6, -2.0, v6
	v_mul_f32_e32 v6, 0x3fb8aa3b, v6
	v_exp_f32_e32 v6, v6
	s_nop 0
	v_add_f32_e32 v6, 1.0, v6
	v_rcp_f32_e32 v6, v6
	s_nop 0
	v_mul_f32_e32 v73, v73, v6
	v_mul_f32_e32 v73, v26, v73
	v_mul_f32_e32 v73, v126, v73
	v_mul_f32_e32 v75, v75, v125
	v_mul_f32_e32 v7, 0x3d372713, v75
	v_mul_f32_e32 v7, v75, v7
	v_fma_f32 v7, v75, v7, v75
	v_mul_f32_e32 v7, 0x3f4c422a, v7
	v_mul_f32_e32 v7, -2.0, v7
	v_mul_f32_e32 v7, 0x3fb8aa3b, v7
	v_exp_f32_e32 v7, v7
	s_nop 0
	v_add_f32_e32 v7, 1.0, v7
	v_rcp_f32_e32 v7, v7
	s_nop 0
	v_mul_f32_e32 v75, v75, v7
	v_mul_f32_e32 v75, v27, v75
	v_mul_f32_e32 v75, v127, v75
	v_mov_b32_e32 v72, v24
	v_mov_b32_e32 v74, v25
	ds_write_b128 v3, v[72:75] offset:1024
	s_waitcnt vmcnt(20)
	v_mul_f32_e32 v77, v77, v128
	v_mul_f32_e32 v6, 0x3d372713, v77
	v_mul_f32_e32 v6, v77, v6
	v_fma_f32 v6, v77, v6, v77
	v_mul_f32_e32 v6, 0x3f4c422a, v6
	v_mul_f32_e32 v6, -2.0, v6
	v_mul_f32_e32 v6, 0x3fb8aa3b, v6
	v_exp_f32_e32 v6, v6
	s_nop 0
	v_add_f32_e32 v6, 1.0, v6
	v_rcp_f32_e32 v6, v6
	s_nop 0
	v_mul_f32_e32 v77, v77, v6
	v_mul_f32_e32 v77, v30, v77
	v_mul_f32_e32 v77, v130, v77
	v_mul_f32_e32 v79, v79, v129
	v_mul_f32_e32 v7, 0x3d372713, v79
	v_mul_f32_e32 v7, v79, v7
	v_fma_f32 v7, v79, v7, v79
	v_mul_f32_e32 v7, 0x3f4c422a, v7
	v_mul_f32_e32 v7, -2.0, v7
	v_mul_f32_e32 v7, 0x3fb8aa3b, v7
	v_exp_f32_e32 v7, v7
	s_nop 0
	v_add_f32_e32 v7, 1.0, v7
	v_rcp_f32_e32 v7, v7
	s_nop 0
	v_mul_f32_e32 v79, v79, v7
	v_mul_f32_e32 v79, v31, v79
	v_mul_f32_e32 v79, v131, v79
	v_mov_b32_e32 v76, v28
	v_mov_b32_e32 v78, v29
	ds_write_b128 v3, v[76:79] offset:2048
	s_waitcnt vmcnt(16)
	v_mul_f32_e32 v81, v81, v132
	v_mul_f32_e32 v6, 0x3d372713, v81
	v_mul_f32_e32 v6, v81, v6
	v_fma_f32 v6, v81, v6, v81
	v_mul_f32_e32 v6, 0x3f4c422a, v6
	v_mul_f32_e32 v6, -2.0, v6
	v_mul_f32_e32 v6, 0x3fb8aa3b, v6
	v_exp_f32_e32 v6, v6
	s_nop 0
	v_add_f32_e32 v6, 1.0, v6
	v_rcp_f32_e32 v6, v6
	s_nop 0
	v_mul_f32_e32 v81, v81, v6
	v_mul_f32_e32 v81, v34, v81
	v_mul_f32_e32 v81, v134, v81
	v_mul_f32_e32 v83, v83, v133
	v_mul_f32_e32 v7, 0x3d372713, v83
	v_mul_f32_e32 v7, v83, v7
	v_fma_f32 v7, v83, v7, v83
	v_mul_f32_e32 v7, 0x3f4c422a, v7
	v_mul_f32_e32 v7, -2.0, v7
	v_mul_f32_e32 v7, 0x3fb8aa3b, v7
	v_exp_f32_e32 v7, v7
	s_nop 0
	v_add_f32_e32 v7, 1.0, v7
	v_rcp_f32_e32 v7, v7
	s_nop 0
	v_mul_f32_e32 v83, v83, v7
	v_mul_f32_e32 v83, v35, v83
	v_mul_f32_e32 v83, v135, v83
	v_mov_b32_e32 v80, v32
	v_mov_b32_e32 v82, v33
	ds_write_b128 v3, v[80:83] offset:3072
	s_waitcnt vmcnt(12)
; DEVI float gelu_f(float x) { const float u = 0.7978845608028654f * (x + 0.044715f * x * x * x); return x * __builtin_amdgcn_rcpf(1.f + __expf(-2.f * u)); }
; #define LAS __attribute__((address_space(3)))
;     ...
;     for (int t = 0; t < NTL; ++t) { const float lo = __shfl_xor(acc[t][0], 32); const float dot = (acc[t][0] + lo * (1.f / 32.f)) * s_u[t];
;         if (kq == 0) pl[t * 16 + n16] = (u32x2_t){(unsigned)e[t], __float_as_uint(g[t] * gelu_f(dot) * s_v[t])}; }
; __global__ void __launch_bounds__(NTHR, 2) mega_fwd(Args a) {
;     ...
; #pragma unroll 1
;               for (int k = 0; k < 8; ++k) { const int tok = gw_ + NGW * (k0 + k);
;                   if (tok < M_P) peer_gather_token_t<8, 2>(q_, l_, 0, -1, (LAS float*)nullptr, GARGS, tok, lane_, (LAS unsigned char*)lds + wave * 8192 + k * 1024); }
	v_mul_f32_e32 v85, v85, v136
	v_mul_f32_e32 v6, 0x3d372713, v85
	v_mul_f32_e32 v6, v85, v6
	v_fma_f32 v6, v85, v6, v85
	v_mul_f32_e32 v6, 0x3f4c422a, v6
	v_mul_f32_e32 v6, -2.0, v6
	v_mul_f32_e32 v6, 0x3fb8aa3b, v6
	v_exp_f32_e32 v6, v6
	s_nop 0
	v_add_f32_e32 v6, 1.0, v6
	v_rcp_f32_e32 v6, v6
	s_nop 0
	v_mul_f32_e32 v85, v85, v6
	v_mul_f32_e32 v85, v38, v85
	v_mul_f32_e32 v85, v138, v85
	v_mul_f32_e32 v87, v87, v137
	v_mul_f32_e32 v7, 0x3d372713, v87
	v_mul_f32_e32 v7, v87, v7
	v_fma_f32 v7, v87, v7, v87
	v_mul_f32_e32 v7, 0x3f4c422a, v7
	v_mul_f32_e32 v7, -2.0, v7
	v_mul_f32_e32 v7, 0x3fb8aa3b, v7
	v_exp_f32_e32 v7, v7
	s_nop 0
	v_add_f32_e32 v7, 1.0, v7
	v_rcp_f32_e32 v7, v7
	s_nop 0
	v_mul_f32_e32 v87, v87, v7
	v_mul_f32_e32 v87, v39, v87
	v_mul_f32_e32 v87, v139, v87
	v_mov_b32_e32 v84, v36
	v_mov_b32_e32 v86, v37
	ds_write_b128 v3, v[84:87] offset:4096
	s_waitcnt vmcnt(8)
	v_mul_f32_e32 v89, v89, v140
	v_mul_f32_e32 v6, 0x3d372713, v89
	v_mul_f32_e32 v6, v89, v6
	v_fma_f32 v6, v89, v6, v89
	v_mul_f32_e32 v6, 0x3f4c422a, v6
	v_mul_f32_e32 v6, -2.0, v6
	v_mul_f32_e32 v6, 0x3fb8aa3b, v6
	v_exp_f32_e32 v6, v6
	s_nop 0
	v_add_f32_e32 v6, 1.0, v6
	v_rcp_f32_e32 v6, v6
	s_nop 0
	v_mul_f32_e32 v89, v89, v6
	v_mul_f32_e32 v89, v42, v89
	v_mul_f32_e32 v89, v142, v89
	v_mul_f32_e32 v91, v91, v141
	v_mul_f32_e32 v7, 0x3d372713, v91
	v_mul_f32_e32 v7, v91, v7
	v_fma_f32 v7, v91, v7, v91
	v_mul_f32_e32 v7, 0x3f4c422a, v7
	v_mul_f32_e32 v7, -2.0, v7
	v_mul_f32_e32 v7, 0x3fb8aa3b, v7
	v_exp_f32_e32 v7, v7
	s_nop 0
	v_add_f32_e32 v7, 1.0, v7
	v_rcp_f32_e32 v7, v7
	s_nop 0
	v_mul_f32_e32 v91, v91, v7
	v_mul_f32_e32 v91, v43, v91
	v_mul_f32_e32 v91, v143, v91
	v_mov_b32_e32 v88, v40
	v_mov_b32_e32 v90, v41
	ds_write_b128 v3, v[88:91] offset:5120
	s_waitcnt vmcnt(4)
	v_mul_f32_e32 v93, v93, v144
	v_mul_f32_e32 v6, 0x3d372713, v93
	v_mul_f32_e32 v6, v93, v6
	v_fma_f32 v6, v93, v6, v93
	v_mul_f32_e32 v6, 0x3f4c422a, v6
	v_mul_f32_e32 v6, -2.0, v6
	v_mul_f32_e32 v6, 0x3fb8aa3b, v6
	v_exp_f32_e32 v6, v6
	s_nop 0
	v_add_f32_e32 v6, 1.0, v6
	v_rcp_f32_e32 v6, v6
	s_nop 0
	v_mul_f32_e32 v93, v93, v6
	v_mul_f32_e32 v93, v46, v93
	v_mul_f32_e32 v93, v146, v93
	v_mul_f32_e32 v95, v95, v145
	v_mul_f32_e32 v7, 0x3d372713, v95
	v_mul_f32_e32 v7, v95, v7
	v_fma_f32 v7, v95, v7, v95
	v_mul_f32_e32 v7, 0x3f4c422a, v7
	v_mul_f32_e32 v7, -2.0, v7
	v_mul_f32_e32 v7, 0x3fb8aa3b, v7
	v_exp_f32_e32 v7, v7
	s_nop 0
	v_add_f32_e32 v7, 1.0, v7
	v_rcp_f32_e32 v7, v7
	s_nop 0
	v_mul_f32_e32 v95, v95, v7
	v_mul_f32_e32 v95, v47, v95
	v_mul_f32_e32 v95, v147, v95
	v_mov_b32_e32 v92, v44
	v_mov_b32_e32 v94, v45
	ds_write_b128 v3, v[92:95] offset:6144
	s_waitcnt vmcnt(0)
	v_mul_f32_e32 v97, v97, v148
	v_mul_f32_e32 v6, 0x3d372713, v97
	v_mul_f32_e32 v6, v97, v6
	v_fma_f32 v6, v97, v6, v97
	v_mul_f32_e32 v6, 0x3f4c422a, v6
	v_mul_f32_e32 v6, -2.0, v6
	v_mul_f32_e32 v6, 0x3fb8aa3b, v6
	v_exp_f32_e32 v6, v6
	s_nop 0
	v_add_f32_e32 v6, 1.0, v6
	v_rcp_f32_e32 v6, v6
	s_nop 0
	v_mul_f32_e32 v97, v97, v6
	v_mul_f32_e32 v97, v50, v97
	v_mul_f32_e32 v97, v150, v97
	v_mul_f32_e32 v99, v99, v149
	v_mul_f32_e32 v7, 0x3d372713, v99
	v_mul_f32_e32 v7, v99, v7
	v_fma_f32 v7, v99, v7, v99
	v_mul_f32_e32 v7, 0x3f4c422a, v7
	v_mul_f32_e32 v7, -2.0, v7
	v_mul_f32_e32 v7, 0x3fb8aa3b, v7
	v_exp_f32_e32 v7, v7
	s_nop 0
	v_add_f32_e32 v7, 1.0, v7
	v_rcp_f32_e32 v7, v7
	s_nop 0
	v_mul_f32_e32 v99, v99, v7
	v_mul_f32_e32 v99, v51, v99
	v_mul_f32_e32 v99, v151, v99
	v_mov_b32_e32 v96, v48
	v_mov_b32_e32 v98, v49
	ds_write_b128 v3, v[96:99] offset:7168
	s_waitcnt lgkmcnt(0)
	v_cmp_gt_u32_e32 vcc, 8, v116
	s_nop 1
	s_ashr_i32 s9, s8, 31
	s_lshl_b64 s[18:19], s[8:9], 24
	s_lshl_b64 s[10:11], s[8:9], 16
	s_add_u32 s9, s6, s10
	s_addc_u32 s13, s7, s11
	s_add_u32 s10, s9, 0x2fa42100
	s_addc_u32 s11, s13, 0
	s_add_u32 s12, s9, 0x2fa82100
	s_addc_u32 s13, s13, 0
	s_add_u32 s14, s6, 0x1b292100
	s_addc_u32 s15, s7, 0
	s_add_u32 s16, s6, 0x1bb12100
	s_addc_u32 s17, s7, 0
	s_add_u32 s18, s6, s18
	s_addc_u32 s19, s7, s19
	v_lshl_add_u64 v[2:3], s[18:19], 0, v[102:103]
	s_mov_b64 s[20:21], 0x1fa42100
	v_lshl_add_u64 v[104:105], v[2:3], 0, s[20:21]
	v_mov_b32_e32 v2, 0x1100000
	v_cndmask_b32_e64 v66, v2, 0, vcc
	v_lshl_add_u64 v[2:3], s[6:7], 0, v[66:67]
	s_add_u32 s49, s6, 0x4000
	v_lshl_add_u64 v[2:3], v[2:3], 0, v[102:103]
	s_mov_b64 s[20:21], 0x2fac2100
	s_addc_u32 s50, s7, 0
	v_lshl_add_u64 v[106:107], v[2:3], 0, s[20:21]
	s_add_u32 s20, s49, s47
	v_lshl_add_u64 v[2:3], s[18:19], 0, v[100:101]
	s_mov_b64 s[18:19], 0x27a42100
	s_addc_u32 s21, s50, s46
	v_lshl_add_u64 v[108:109], v[2:3], 0, s[18:19]
	v_lshlrev_b64 v[2:3], 2, v[100:101]
	v_lshl_add_u64 v[4:5], s[20:21], 0, v[2:3]
	s_mov_b64 s[18:19], 0x5000
	s_cmp_lt_i32 s8, 3
	v_lshl_add_u64 v[110:111], v[4:5], 0, s[18:19]
	s_cselect_b64 s[18:19], -1, 0
	s_add_i32 s24, s8, 1
	s_ashr_i32 s25, s24, 31
	s_lshl_b64 s[20:21], s[24:25], 12
	s_add_u32 s55, s6, 0x20e100
	s_addc_u32 s56, s7, 0
	s_lshl_b32 s26, s24, 2
	s_ashr_i32 s27, s26, 31
	s_mul_i32 s23, s24, 0xc000
	s_mul_hi_i32 s22, s24, 0xc000
	s_add_u32 s23, s6, s23
	s_addc_u32 s28, s7, s22
	s_add_u32 s22, s23, 0x1f812100
	s_addc_u32 s23, s28, 0
	s_add_u32 s57, s6, 0xcb8a100
	s_addc_u32 s58, s7, 0
	s_lshl_b64 s[28:29], s[24:25], 18
	s_add_u32 s59, s4, s28
	s_addc_u32 s60, s5, s29
	s_lshl_b32 s28, s24, 3
	s_ashr_i32 s29, s28, 31
	s_add_u32 s61, s6, 0xacda100
	s_mov_b32 s9, 0
	v_lshl_add_u64 v[112:113], s[4:5], 0, v[2:3]
	s_mul_hi_i32 s51, s24, 18
	s_mul_i32 s54, s24, 18
	s_addc_u32 s62, s7, 0
	s_lshl_b64 s[24:25], s[26:27], 2
	s_lshl_b64 s[26:27], s[28:29], 2
	s_mov_b32 s63, s48
	s_branch .LBB0_1087
